# v32 + batched gate-row and residual-row load ladders in the merge / residual GEMM epilogues + RWKV stage LDS-read batching + prep boundary waits dropped (all the individually sound latency edits toget
# speedup vs baseline: 1.0187x; 1.0187x over previous
; __device__ __forceinline__ uint4 pack_acc8(const f32x4 a, const f32x4 b, float s) { uint4 w; w.x = cvt_pk_bf16(a[0] * s, a[1] * s); w.y = cvt_pk_bf16(a[2] * s, a[3] * s); w.z = cvt_pk_bf16(b[0] * s, b[1] * s); w.w = cvt_pk_bf16(b[2] * s, b[3] * s); return w; }
;     __device__ __forceinline__ void operator()(AccM acc, const Unit& u, int wr, int wc, int fr, int fq) const {
;         const int row0 = u.pm * BM + wr * 64 + fr, col0 = u.pn * HALF + wc * 32 + 8 * fq;
;         const bf16_t* gb = G + (size_t)row0 * 3072 + u.z * 1024 + col0;
;         bf16_t* mb = MB + (size_t)row0 * D_ + col0;
;         const int z = u.z;
; #pragma unroll
;         for (int ai = 0; ai < 2; ++ai)
; #pragma unroll
;             for (int m = 0; m < 4; ++m) {
;                 const u32x4 gr_ = __builtin_nontemporal_load((const u32x4*)(gb + (size_t)(ai * HALF + m * 16) * 3072)); const uint4 gr = make_uint4(gr_[0], gr_[1], gr_[2], gr_[3]); float gf[8]; unpack8(gr, gf);
;                 f32x4 v0, v1;
; #pragma unroll
;                 for (int j = 0; j < 4; ++j) { v0[j] = gf[j] * acc[ai][0][m][0][j]; v1[j] = gf[4 + j] * acc[ai][0][m][1][j]; }
;                 if (z > 0) { v0 += acc[ai][1][m][0]; v1 += acc[ai][1][m][1]; }
;                 acc[ai][1][m][0] = v0; acc[ai][1][m][1] = v1;
;                 if (z == 2) *(uint4*)(mb + (size_t)(ai * HALF + m * 16) * D_) = pack_acc8(v0, v1, 1.0f);
;                 asm volatile("" ::: "memory");
;             }
.LBB0_141:
	v_readlane_b32 s4, v254, 35
	v_readlane_b32 s5, v254, 36
	v_lshl_add_u32 v138, s64, 8, v162
	v_lshl_or_b32 v158, s63, 7, v164
	v_mov_b64_e32 v[160:161], s[4:5]
	s_movk_i32 s4, 0x1800
	v_mad_i64_i32 v[160:161], s[4:5], v138, s4, v[160:161]
	s_lshl_b32 s4, s65, 10
	s_ashr_i32 s5, s4, 31
	v_ashrrev_i32_e32 v159, 31, v158
	v_lshl_add_u64 v[160:161], s[4:5], 1, v[160:161]
	v_lshlrev_b64 v[158:159], 1, v[158:159]
	v_lshl_add_u64 v[160:161], v[160:161], 0, v[158:159]
	global_load_dwordx4 v[180:183], v[160:161], off nt
	v_add_co_u32_e32 v220, vcc, 0x18000, v160
	s_nop 1
	v_addc_co_u32_e32 v221, vcc, 0, v161, vcc
	global_load_dwordx4 v[192:195], v[220:221], off nt
	v_add_co_u32_e32 v222, vcc, 0x30000, v160
	s_nop 1
	v_addc_co_u32_e32 v223, vcc, 0, v161, vcc
	global_load_dwordx4 v[196:199], v[222:223], off nt
	v_add_co_u32_e32 v220, vcc, 0x48000, v160
	s_nop 1
	v_addc_co_u32_e32 v221, vcc, 0, v161, vcc
	global_load_dwordx4 v[200:203], v[220:221], off nt
	v_add_co_u32_e32 v222, vcc, 0xc0000, v160
	s_nop 1
	v_addc_co_u32_e32 v223, vcc, 0, v161, vcc
	global_load_dwordx4 v[204:207], v[222:223], off nt
	v_add_co_u32_e32 v220, vcc, 0xd8000, v160
	s_nop 1
	v_addc_co_u32_e32 v221, vcc, 0, v161, vcc
	global_load_dwordx4 v[208:211], v[220:221], off nt
	v_add_co_u32_e32 v222, vcc, 0xf0000, v160
	s_nop 1
	v_addc_co_u32_e32 v223, vcc, 0, v161, vcc
	global_load_dwordx4 v[212:215], v[222:223], off nt
	v_add_co_u32_e32 v220, vcc, 0x108000, v160
	s_nop 1
	v_addc_co_u32_e32 v221, vcc, 0, v161, vcc
	global_load_dwordx4 v[216:219], v[220:221], off nt
	v_ashrrev_i32_e32 v139, 31, v138
	v_readlane_b32 s4, v254, 33
	v_lshlrev_b64 v[138:139], 11, v[138:139]
	v_readlane_b32 s5, v254, 34
	s_cmp_gt_i32 s65, 0
	s_waitcnt vmcnt(7) lgkmcnt(0)
	v_lshlrev_b32_e32 v166, 16, v182
	v_lshl_add_u64 v[138:139], s[4:5], 0, v[138:139]
	v_lshl_add_u64 v[158:159], v[138:139], 0, v[158:159]
	v_lshlrev_b32_e32 v138, 16, v180
	v_and_b32_e32 v139, 0xffff0000, v180
	v_and_b32_e32 v167, 0xffff0000, v182
	v_lshlrev_b32_e32 v178, 16, v181
	v_and_b32_e32 v179, 0xffff0000, v181
	v_lshlrev_b32_e32 v180, 16, v183
	v_and_b32_e32 v181, 0xffff0000, v183
	v_pk_mul_f32 v[182:183], v[64:65], v[180:181]
	v_pk_fma_f32 v[64:65], v[64:65], v[180:181], v[156:157]
	s_cselect_b64 s[4:5], -1, 0
	s_cmp_eq_u32 s65, 2
	v_pk_mul_f32 v[180:181], v[58:59], v[138:139]
	v_pk_mul_f32 v[184:185], v[62:63], v[166:167]
	v_pk_mul_f32 v[186:187], v[60:61], v[178:179]
	v_pk_fma_f32 v[60:61], v[60:61], v[178:179], v[154:155]
	v_pk_fma_f32 v[58:59], v[58:59], v[138:139], v[152:153]
	v_pk_fma_f32 v[62:63], v[62:63], v[166:167], v[150:151]
	s_cselect_b64 s[24:25], -1, 0
	s_cmp_lg_u32 s65, 2
	v_cndmask_b32_e64 v157, v183, v65, s[4:5]
	v_cndmask_b32_e64 v156, v182, v64, s[4:5]
	v_cndmask_b32_e64 v151, v185, v63, s[4:5]
	v_cndmask_b32_e64 v150, v184, v62, s[4:5]
	v_cndmask_b32_e64 v155, v187, v61, s[4:5]
	v_cndmask_b32_e64 v154, v186, v60, s[4:5]
	v_cndmask_b32_e64 v153, v181, v59, s[4:5]
	v_cndmask_b32_e64 v152, v180, v58, s[4:5]
.LBB0_143:
	v_cndmask_b32_e64 v222, 0, 1, s[24:25]
	v_cmp_ne_u32_e64 s[6:7], 1, v222
	s_waitcnt vmcnt(6)
	v_lshlrev_b32_e32 v62, 16, v192
	v_and_b32_e32 v63, 0xffff0000, v192
	v_lshlrev_b32_e32 v64, 16, v194
	v_and_b32_e32 v65, 0xffff0000, v194
	v_lshlrev_b32_e32 v58, 16, v193
	v_and_b32_e32 v59, 0xffff0000, v193
	v_lshlrev_b32_e32 v60, 16, v195
	v_and_b32_e32 v61, 0xffff0000, v195
	v_pk_mul_f32 v[138:139], v[54:55], v[62:63]
	v_pk_mul_f32 v[166:167], v[50:51], v[64:65]
	v_pk_mul_f32 v[178:179], v[56:57], v[58:59]
	v_pk_mul_f32 v[180:181], v[52:53], v[60:61]
	v_pk_fma_f32 v[56:57], v[56:57], v[58:59], v[148:149]
	v_pk_fma_f32 v[54:55], v[54:55], v[62:63], v[128:129]
	v_pk_fma_f32 v[52:53], v[52:53], v[60:61], v[122:123]
	v_pk_fma_f32 v[50:51], v[50:51], v[64:65], v[120:121]
	v_cndmask_b32_e64 v123, v181, v53, s[4:5]
	v_cndmask_b32_e64 v122, v180, v52, s[4:5]
	v_cndmask_b32_e64 v121, v167, v51, s[4:5]
	v_cndmask_b32_e64 v120, v166, v50, s[4:5]
	v_cndmask_b32_e64 v149, v179, v57, s[4:5]
	v_cndmask_b32_e64 v148, v178, v56, s[4:5]
	v_cndmask_b32_e64 v129, v139, v55, s[4:5]
	v_cndmask_b32_e64 v128, v138, v54, s[4:5]
.LBB0_145:
	s_waitcnt vmcnt(5)
	v_lshlrev_b32_e32 v54, 16, v196
	v_and_b32_e32 v55, 0xffff0000, v196
	v_lshlrev_b32_e32 v56, 16, v198
	v_and_b32_e32 v57, 0xffff0000, v198
	v_lshlrev_b32_e32 v50, 16, v197
	v_and_b32_e32 v51, 0xffff0000, v197
	v_lshlrev_b32_e32 v52, 16, v199
	v_and_b32_e32 v53, 0xffff0000, v199
	v_pk_mul_f32 v[58:59], v[46:47], v[54:55]
	v_pk_mul_f32 v[60:61], v[42:43], v[56:57]
	v_pk_mul_f32 v[62:63], v[48:49], v[50:51]
	v_pk_mul_f32 v[64:65], v[44:45], v[52:53]
	v_pk_fma_f32 v[48:49], v[48:49], v[50:51], v[126:127]
	v_pk_fma_f32 v[46:47], v[46:47], v[54:55], v[124:125]
	v_pk_fma_f32 v[44:45], v[44:45], v[52:53], v[114:115]
	v_pk_fma_f32 v[42:43], v[42:43], v[56:57], v[112:113]
	v_cndmask_b32_e64 v115, v65, v45, s[4:5]
	v_cndmask_b32_e64 v114, v64, v44, s[4:5]
	v_cndmask_b32_e64 v113, v61, v43, s[4:5]
	v_cndmask_b32_e64 v112, v60, v42, s[4:5]
	v_cndmask_b32_e64 v127, v63, v49, s[4:5]
	v_cndmask_b32_e64 v126, v62, v48, s[4:5]
	v_cndmask_b32_e64 v125, v59, v47, s[4:5]
	v_cndmask_b32_e64 v124, v58, v46, s[4:5]
; __device__ __forceinline__ uint4 pack_acc8(const f32x4 a, const f32x4 b, float s) { uint4 w; w.x = cvt_pk_bf16(a[0] * s, a[1] * s); w.y = cvt_pk_bf16(a[2] * s, a[3] * s); w.z = cvt_pk_bf16(b[0] * s, b[1] * s); w.w = cvt_pk_bf16(b[2] * s, b[3] * s); return w; }
;     __device__ __forceinline__ void operator()(AccM acc, const Unit& u, int wr, int wc, int fr, int fq) const {
;         const int row0 = u.pm * BM + wr * 64 + fr, col0 = u.pn * HALF + wc * 32 + 8 * fq;
;         const bf16_t* gb = G + (size_t)row0 * 3072 + u.z * 1024 + col0;
;         bf16_t* mb = MB + (size_t)row0 * D_ + col0;
;         const int z = u.z;
; #pragma unroll
;         for (int ai = 0; ai < 2; ++ai)
; #pragma unroll
;             for (int m = 0; m < 4; ++m) {
;                 const u32x4 gr_ = __builtin_nontemporal_load((const u32x4*)(gb + (size_t)(ai * HALF + m * 16) * 3072)); const uint4 gr = make_uint4(gr_[0], gr_[1], gr_[2], gr_[3]); float gf[8]; unpack8(gr, gf);
;                 f32x4 v0, v1;
; #pragma unroll
;                 for (int j = 0; j < 4; ++j) { v0[j] = gf[j] * acc[ai][0][m][0][j]; v1[j] = gf[4 + j] * acc[ai][0][m][1][j]; }
;                 if (z > 0) { v0 += acc[ai][1][m][0]; v1 += acc[ai][1][m][1]; }
;                 acc[ai][1][m][0] = v0; acc[ai][1][m][1] = v1;
;                 if (z == 2) *(uint4*)(mb + (size_t)(ai * HALF + m * 16) * D_) = pack_acc8(v0, v1, 1.0f);
;                 asm volatile("" ::: "memory");
;             }
.LBB0_147:
	s_waitcnt vmcnt(4)
	v_lshlrev_b32_e32 v46, 16, v200
	v_and_b32_e32 v47, 0xffff0000, v200
	v_lshlrev_b32_e32 v48, 16, v202
	v_and_b32_e32 v49, 0xffff0000, v202
	v_lshlrev_b32_e32 v42, 16, v201
	v_and_b32_e32 v43, 0xffff0000, v201
	v_lshlrev_b32_e32 v44, 16, v203
	v_and_b32_e32 v45, 0xffff0000, v203
	v_pk_mul_f32 v[50:51], v[38:39], v[46:47]
	v_pk_mul_f32 v[52:53], v[34:35], v[48:49]
	v_pk_mul_f32 v[54:55], v[40:41], v[42:43]
	v_pk_mul_f32 v[56:57], v[36:37], v[44:45]
	v_pk_fma_f32 v[40:41], v[40:41], v[42:43], v[118:119]
	v_pk_fma_f32 v[38:39], v[38:39], v[46:47], v[116:117]
	v_pk_fma_f32 v[36:37], v[36:37], v[44:45], v[106:107]
	v_pk_fma_f32 v[34:35], v[34:35], v[48:49], v[104:105]
	v_cndmask_b32_e64 v107, v57, v37, s[4:5]
	v_cndmask_b32_e64 v106, v56, v36, s[4:5]
	v_cndmask_b32_e64 v105, v53, v35, s[4:5]
	v_cndmask_b32_e64 v104, v52, v34, s[4:5]
	v_cndmask_b32_e64 v119, v55, v41, s[4:5]
	v_cndmask_b32_e64 v118, v54, v40, s[4:5]
	v_cndmask_b32_e64 v117, v51, v39, s[4:5]
	v_cndmask_b32_e64 v116, v50, v38, s[4:5]
.LBB0_149:
	s_waitcnt vmcnt(3)
	v_lshlrev_b32_e32 v38, 16, v204
	v_and_b32_e32 v39, 0xffff0000, v204
	v_lshlrev_b32_e32 v40, 16, v206
	v_and_b32_e32 v41, 0xffff0000, v206
	v_lshlrev_b32_e32 v34, 16, v205
	v_and_b32_e32 v35, 0xffff0000, v205
	v_lshlrev_b32_e32 v36, 16, v207
	v_and_b32_e32 v37, 0xffff0000, v207
	v_pk_mul_f32 v[42:43], v[30:31], v[38:39]
	v_pk_mul_f32 v[44:45], v[26:27], v[40:41]
	v_pk_mul_f32 v[46:47], v[32:33], v[34:35]
	v_pk_mul_f32 v[48:49], v[28:29], v[36:37]
	v_pk_fma_f32 v[32:33], v[32:33], v[34:35], v[110:111]
	v_pk_fma_f32 v[30:31], v[30:31], v[38:39], v[108:109]
	v_pk_fma_f32 v[28:29], v[28:29], v[36:37], v[98:99]
	v_pk_fma_f32 v[26:27], v[26:27], v[40:41], v[96:97]
	v_cndmask_b32_e64 v99, v49, v29, s[4:5]
	v_cndmask_b32_e64 v98, v48, v28, s[4:5]
	v_cndmask_b32_e64 v97, v45, v27, s[4:5]
	v_cndmask_b32_e64 v96, v44, v26, s[4:5]
	v_cndmask_b32_e64 v111, v47, v33, s[4:5]
	v_cndmask_b32_e64 v110, v46, v32, s[4:5]
	v_cndmask_b32_e64 v109, v43, v31, s[4:5]
	v_cndmask_b32_e64 v108, v42, v30, s[4:5]
.LBB0_151:
	s_waitcnt vmcnt(2)
	v_lshlrev_b32_e32 v30, 16, v208
	v_and_b32_e32 v31, 0xffff0000, v208
	v_lshlrev_b32_e32 v32, 16, v210
	v_and_b32_e32 v33, 0xffff0000, v210
	v_lshlrev_b32_e32 v26, 16, v209
	v_and_b32_e32 v27, 0xffff0000, v209
	v_lshlrev_b32_e32 v28, 16, v211
	v_and_b32_e32 v29, 0xffff0000, v211
	v_pk_mul_f32 v[34:35], v[22:23], v[30:31]
	v_pk_mul_f32 v[36:37], v[18:19], v[32:33]
	v_pk_mul_f32 v[38:39], v[24:25], v[26:27]
	v_pk_mul_f32 v[40:41], v[20:21], v[28:29]
	v_pk_fma_f32 v[24:25], v[24:25], v[26:27], v[102:103]
	v_pk_fma_f32 v[22:23], v[22:23], v[30:31], v[100:101]
	v_pk_fma_f32 v[20:21], v[20:21], v[28:29], v[90:91]
	v_pk_fma_f32 v[18:19], v[18:19], v[32:33], v[88:89]
	v_cndmask_b32_e64 v91, v41, v21, s[4:5]
	v_cndmask_b32_e64 v90, v40, v20, s[4:5]
	v_cndmask_b32_e64 v89, v37, v19, s[4:5]
	v_cndmask_b32_e64 v88, v36, v18, s[4:5]
	v_cndmask_b32_e64 v103, v39, v25, s[4:5]
	v_cndmask_b32_e64 v102, v38, v24, s[4:5]
	v_cndmask_b32_e64 v101, v35, v23, s[4:5]
	v_cndmask_b32_e64 v100, v34, v22, s[4:5]
; __device__ __forceinline__ uint4 pack_acc8(const f32x4 a, const f32x4 b, float s) { uint4 w; w.x = cvt_pk_bf16(a[0] * s, a[1] * s); w.y = cvt_pk_bf16(a[2] * s, a[3] * s); w.z = cvt_pk_bf16(b[0] * s, b[1] * s); w.w = cvt_pk_bf16(b[2] * s, b[3] * s); return w; }
;     __device__ __forceinline__ void operator()(AccM acc, const Unit& u, int wr, int wc, int fr, int fq) const {
;         const int row0 = u.pm * BM + wr * 64 + fr, col0 = u.pn * HALF + wc * 32 + 8 * fq;
;         const bf16_t* gb = G + (size_t)row0 * 3072 + u.z * 1024 + col0;
;         bf16_t* mb = MB + (size_t)row0 * D_ + col0;
;         const int z = u.z;
; #pragma unroll
;         for (int ai = 0; ai < 2; ++ai)
; #pragma unroll
;             for (int m = 0; m < 4; ++m) {
;                 const u32x4 gr_ = __builtin_nontemporal_load((const u32x4*)(gb + (size_t)(ai * HALF + m * 16) * 3072)); const uint4 gr = make_uint4(gr_[0], gr_[1], gr_[2], gr_[3]); float gf[8]; unpack8(gr, gf);
;                 f32x4 v0, v1;
; #pragma unroll
;                 for (int j = 0; j < 4; ++j) { v0[j] = gf[j] * acc[ai][0][m][0][j]; v1[j] = gf[4 + j] * acc[ai][0][m][1][j]; }
;                 if (z > 0) { v0 += acc[ai][1][m][0]; v1 += acc[ai][1][m][1]; }
;                 acc[ai][1][m][0] = v0; acc[ai][1][m][1] = v1;
;                 if (z == 2) *(uint4*)(mb + (size_t)(ai * HALF + m * 16) * D_) = pack_acc8(v0, v1, 1.0f);
;                 asm volatile("" ::: "memory");
;             }
.LBB0_153:
	s_waitcnt vmcnt(1)
	v_lshlrev_b32_e32 v22, 16, v212
	v_and_b32_e32 v23, 0xffff0000, v212
	v_lshlrev_b32_e32 v24, 16, v214
	v_and_b32_e32 v25, 0xffff0000, v214
	v_lshlrev_b32_e32 v18, 16, v213
	v_and_b32_e32 v19, 0xffff0000, v213
	v_lshlrev_b32_e32 v20, 16, v215
	v_and_b32_e32 v21, 0xffff0000, v215
	v_pk_mul_f32 v[26:27], v[14:15], v[22:23]
	v_pk_mul_f32 v[28:29], v[10:11], v[24:25]
	v_pk_mul_f32 v[30:31], v[16:17], v[18:19]
	v_pk_mul_f32 v[32:33], v[12:13], v[20:21]
	v_pk_fma_f32 v[16:17], v[16:17], v[18:19], v[94:95]
	v_pk_fma_f32 v[14:15], v[14:15], v[22:23], v[92:93]
	v_pk_fma_f32 v[12:13], v[12:13], v[20:21], v[82:83]
	v_pk_fma_f32 v[10:11], v[10:11], v[24:25], v[80:81]
	v_cndmask_b32_e64 v83, v33, v13, s[4:5]
	v_cndmask_b32_e64 v82, v32, v12, s[4:5]
	v_cndmask_b32_e64 v81, v29, v11, s[4:5]
	v_cndmask_b32_e64 v80, v28, v10, s[4:5]
	v_cndmask_b32_e64 v95, v31, v17, s[4:5]
	v_cndmask_b32_e64 v94, v30, v16, s[4:5]
	v_cndmask_b32_e64 v93, v27, v15, s[4:5]
	v_cndmask_b32_e64 v92, v26, v14, s[4:5]
.LBB0_155:
	s_waitcnt vmcnt(0)
	v_lshlrev_b32_e32 v14, 16, v216
	v_and_b32_e32 v15, 0xffff0000, v216
	v_lshlrev_b32_e32 v16, 16, v218
	v_and_b32_e32 v17, 0xffff0000, v218
	v_lshlrev_b32_e32 v10, 16, v217
	v_and_b32_e32 v11, 0xffff0000, v217
	v_lshlrev_b32_e32 v12, 16, v219
	v_and_b32_e32 v13, 0xffff0000, v219
	v_pk_mul_f32 v[18:19], v[6:7], v[14:15]
	v_pk_mul_f32 v[20:21], v[2:3], v[16:17]
	v_pk_mul_f32 v[22:23], v[8:9], v[10:11]
	v_pk_mul_f32 v[24:25], v[4:5], v[12:13]
	v_pk_fma_f32 v[8:9], v[8:9], v[10:11], v[86:87]
	v_pk_fma_f32 v[6:7], v[6:7], v[14:15], v[84:85]
	v_pk_fma_f32 v[4:5], v[4:5], v[12:13], v[78:79]
	v_pk_fma_f32 v[2:3], v[2:3], v[16:17], v[76:77]
	v_cndmask_b32_e64 v79, v25, v5, s[4:5]
	v_cndmask_b32_e64 v78, v24, v4, s[4:5]
	v_cndmask_b32_e64 v77, v21, v3, s[4:5]
	v_cndmask_b32_e64 v76, v20, v2, s[4:5]
	v_cndmask_b32_e64 v87, v23, v9, s[4:5]
	v_cndmask_b32_e64 v86, v22, v8, s[4:5]
	v_cndmask_b32_e64 v85, v19, v7, s[4:5]
	v_cndmask_b32_e64 v84, v18, v6, s[4:5]
	s_cmp_lg_u32 s65, 2
	s_cbranch_scc1 .LBB0_157
	v_cvt_pk_bf16_f32 v58, v152, v153
	v_cvt_pk_bf16_f32 v59, v154, v155
	v_cvt_pk_bf16_f32 v60, v150, v151
	v_cvt_pk_bf16_f32 v61, v156, v157
	global_store_dwordx4 v[158:159], v[58:61], off
	v_add_co_u32_e32 v54, vcc, 0x8000, v158
	v_cvt_pk_bf16_f32 v50, v128, v129
	v_cvt_pk_bf16_f32 v51, v148, v149
	v_cvt_pk_bf16_f32 v52, v120, v121
	v_cvt_pk_bf16_f32 v53, v122, v123
	v_addc_co_u32_e32 v55, vcc, 0, v159, vcc
	global_store_dwordx4 v[54:55], v[50:53], off
	v_add_co_u32_e32 v46, vcc, 0x10000, v158
	v_cvt_pk_bf16_f32 v42, v124, v125
	v_cvt_pk_bf16_f32 v43, v126, v127
	v_cvt_pk_bf16_f32 v44, v112, v113
	v_cvt_pk_bf16_f32 v45, v114, v115
	v_addc_co_u32_e32 v47, vcc, 0, v159, vcc
	global_store_dwordx4 v[46:47], v[42:45], off
	v_add_co_u32_e32 v38, vcc, 0x18000, v158
	v_cvt_pk_bf16_f32 v34, v116, v117
	v_cvt_pk_bf16_f32 v35, v118, v119
	v_cvt_pk_bf16_f32 v36, v104, v105
	v_cvt_pk_bf16_f32 v37, v106, v107
	v_addc_co_u32_e32 v39, vcc, 0, v159, vcc
	global_store_dwordx4 v[38:39], v[34:37], off
	v_add_co_u32_e32 v30, vcc, 0x40000, v158
	v_cvt_pk_bf16_f32 v26, v108, v109
	v_cvt_pk_bf16_f32 v27, v110, v111
	v_cvt_pk_bf16_f32 v28, v96, v97
	v_cvt_pk_bf16_f32 v29, v98, v99
	v_addc_co_u32_e32 v31, vcc, 0, v159, vcc
	global_store_dwordx4 v[30:31], v[26:29], off
	v_add_co_u32_e32 v22, vcc, 0x48000, v158
	v_cvt_pk_bf16_f32 v18, v100, v101
	v_cvt_pk_bf16_f32 v19, v102, v103
	v_cvt_pk_bf16_f32 v20, v88, v89
	v_cvt_pk_bf16_f32 v21, v90, v91
	v_addc_co_u32_e32 v23, vcc, 0, v159, vcc
	global_store_dwordx4 v[22:23], v[18:21], off
	v_add_co_u32_e32 v14, vcc, 0x50000, v158
	v_cvt_pk_bf16_f32 v10, v92, v93
	v_cvt_pk_bf16_f32 v11, v94, v95
	v_cvt_pk_bf16_f32 v12, v80, v81
	v_cvt_pk_bf16_f32 v13, v82, v83
	v_addc_co_u32_e32 v15, vcc, 0, v159, vcc
	global_store_dwordx4 v[14:15], v[10:13], off
	v_add_co_u32_e32 v6, vcc, 0x58000, v158
	v_cvt_pk_bf16_f32 v2, v84, v85
	v_cvt_pk_bf16_f32 v3, v86, v87
	v_cvt_pk_bf16_f32 v4, v76, v77
	v_cvt_pk_bf16_f32 v5, v78, v79
	v_addc_co_u32_e32 v7, vcc, 0, v159, vcc
	global_store_dwordx4 v[6:7], v[2:5], off
